# NA attention: counted per-MFMA waits in PV and removal of the per-tile accumulator copies in the NA row-tile loop, on top of v74
# speedup vs baseline: 1.1435x; 1.0065x over previous
.LBB0_181:
	v_add_u32_e32 v80, s39, v135
	ds_read_b64_tr_b16 v[68:69], v80 offset:0
	ds_read_b64_tr_b16 v[70:71], v80 offset:0x400
	ds_read_b64_tr_b16 v[72:73], v80 offset:0x800
	ds_read_b64_tr_b16 v[74:75], v80 offset:0xc00
	ds_read_b64_tr_b16 v[76:77], v80 offset:0x1000
	ds_read_b64_tr_b16 v[78:79], v80 offset:0x1400
	ds_read_b64_tr_b16 v[174:175], v80 offset:0x1800
	ds_read_b64_tr_b16 v[176:177], v80 offset:0x1c00
	s_nop 0
	s_waitcnt lgkmcnt(6)
	v_mfma_f32_32x32x16_bf16 v[2:17], v[62:65], v[68:71], v[2:17]
	ds_read_b64_tr_b16 v[68:69], v80 offset:0x200
	ds_read_b64_tr_b16 v[70:71], v80 offset:0x600
	s_waitcnt lgkmcnt(6)
	v_mfma_f32_32x32x16_bf16 v[2:17], v[58:61], v[72:75], v[2:17]
	ds_read_b64_tr_b16 v[72:73], v80 offset:0xa00
	ds_read_b64_tr_b16 v[74:75], v80 offset:0xe00
	s_waitcnt lgkmcnt(6)
	v_mfma_f32_32x32x16_bf16 v[2:17], v[54:57], v[76:79], v[2:17]
	ds_read_b64_tr_b16 v[76:77], v80 offset:0x1200
	ds_read_b64_tr_b16 v[78:79], v80 offset:0x1600
	s_waitcnt lgkmcnt(6)
	v_mfma_f32_32x32x16_bf16 v[2:17], v[50:53], v[174:177], v[2:17]
	ds_read_b64_tr_b16 v[174:175], v80 offset:0x1a00
	ds_read_b64_tr_b16 v[176:177], v80 offset:0x1e00
	s_waitcnt lgkmcnt(6)
	v_mfma_f32_32x32x16_bf16 v[18:33], v[62:65], v[68:71], v[18:33]
	s_andn2_b64 vcc, exec, s[8:9]
	s_waitcnt lgkmcnt(4)
	v_mfma_f32_32x32x16_bf16 v[18:33], v[58:61], v[72:75], v[18:33]
	s_waitcnt lgkmcnt(2)
	v_mfma_f32_32x32x16_bf16 v[18:33], v[54:57], v[76:79], v[18:33]
	s_waitcnt lgkmcnt(0)
	v_mfma_f32_32x32x16_bf16 v[18:33], v[50:53], v[174:177], v[18:33]
	s_cbranch_vccnz .LBB0_173
	s_xor_b32 s8, s39, 0x2000
	v_add_u32_e32 v51, s8, v113
	v_add_u32_e32 v50, s8, v117
	s_waitcnt vmcnt(0)
	ds_write_b128 v51, v[102:105]
	ds_write_b128 v50, v[98:101] offset:16384
	s_branch .LBB0_173

.LBB0_213:
	ds_read_b64_tr_b16 v[54:55], v139 offset:0
	ds_read_b64_tr_b16 v[56:57], v139 offset:0x400
	ds_read_b64_tr_b16 v[58:59], v139 offset:0x800
	ds_read_b64_tr_b16 v[60:61], v139 offset:0xc00
	ds_read_b64_tr_b16 v[62:63], v139 offset:0x1000
	ds_read_b64_tr_b16 v[64:65], v139 offset:0x1400
	ds_read_b64_tr_b16 v[66:67], v139 offset:0x1800
	ds_read_b64_tr_b16 v[68:69], v139 offset:0x1c00
	s_nop 0
	s_waitcnt lgkmcnt(6)
	v_mfma_f32_32x32x16_bf16 v[2:17], v[50:53], v[54:57], v[2:17]
	ds_read_b64_tr_b16 v[54:55], v139 offset:0x200
	ds_read_b64_tr_b16 v[56:57], v139 offset:0x600
	s_waitcnt lgkmcnt(6)
	v_mfma_f32_32x32x16_bf16 v[2:17], v[46:49], v[58:61], v[2:17]
	ds_read_b64_tr_b16 v[58:59], v139 offset:0xa00
	ds_read_b64_tr_b16 v[60:61], v139 offset:0xe00
	s_waitcnt lgkmcnt(6)
	v_mfma_f32_32x32x16_bf16 v[2:17], v[42:45], v[62:65], v[2:17]
	ds_read_b64_tr_b16 v[62:63], v139 offset:0x1200
	ds_read_b64_tr_b16 v[64:65], v139 offset:0x1600
	s_waitcnt lgkmcnt(6)
	v_mfma_f32_32x32x16_bf16 v[2:17], v[38:41], v[66:69], v[2:17]
	ds_read_b64_tr_b16 v[66:67], v139 offset:0x1a00
	ds_read_b64_tr_b16 v[68:69], v139 offset:0x1e00
	s_waitcnt lgkmcnt(6)
	v_mfma_f32_32x32x16_bf16 v[18:33], v[50:53], v[54:57], v[18:33]
	s_andn2_b64 vcc, exec, s[74:75]
	s_waitcnt lgkmcnt(4)
	v_mfma_f32_32x32x16_bf16 v[18:33], v[46:49], v[58:61], v[18:33]
	s_waitcnt lgkmcnt(2)
	v_mfma_f32_32x32x16_bf16 v[18:33], v[42:45], v[62:65], v[18:33]
	s_waitcnt lgkmcnt(0)
	v_mfma_f32_32x32x16_bf16 v[18:33], v[38:41], v[66:69], v[18:33]
	s_cbranch_vccnz .LBB0_215
	s_waitcnt vmcnt(0)
	ds_write_b128 v113, v[104:107]
	ds_write_b128 v117, v[100:103] offset:16384

.LBB0_223:
	ds_read_b64_tr_b16 v[70:71], v135 offset:0
	ds_read_b64_tr_b16 v[72:73], v135 offset:0x400
	ds_read_b64_tr_b16 v[74:75], v135 offset:0x800
	ds_read_b64_tr_b16 v[76:77], v135 offset:0xc00
	ds_read_b64_tr_b16 v[78:79], v135 offset:0x1000
	ds_read_b64_tr_b16 v[80:81], v135 offset:0x1400
	ds_read_b64_tr_b16 v[180:181], v135 offset:0x1800
	ds_read_b64_tr_b16 v[182:183], v135 offset:0x1c00
	s_nop 0
	s_waitcnt lgkmcnt(6)
	v_mfma_f32_32x32x16_bf16 v[2:17], v[64:67], v[70:73], v[2:17]
	ds_read_b64_tr_b16 v[70:71], v135 offset:0x200
	ds_read_b64_tr_b16 v[72:73], v135 offset:0x600
	s_waitcnt lgkmcnt(6)
	v_mfma_f32_32x32x16_bf16 v[2:17], v[60:63], v[74:77], v[2:17]
	ds_read_b64_tr_b16 v[74:75], v135 offset:0xa00
	ds_read_b64_tr_b16 v[76:77], v135 offset:0xe00
	s_waitcnt lgkmcnt(6)
	v_mfma_f32_32x32x16_bf16 v[2:17], v[56:59], v[78:81], v[2:17]
	ds_read_b64_tr_b16 v[78:79], v135 offset:0x1200
	ds_read_b64_tr_b16 v[80:81], v135 offset:0x1600
	s_waitcnt lgkmcnt(6)
	v_mfma_f32_32x32x16_bf16 v[2:17], v[52:55], v[180:183], v[2:17]
	ds_read_b64_tr_b16 v[180:181], v135 offset:0x1a00
	ds_read_b64_tr_b16 v[182:183], v135 offset:0x1e00
	s_waitcnt lgkmcnt(6)
	v_mfma_f32_32x32x16_bf16 v[18:33], v[64:67], v[70:73], v[18:33]
	s_andn2_b64 vcc, exec, s[74:75]
	s_waitcnt lgkmcnt(4)
	v_mfma_f32_32x32x16_bf16 v[18:33], v[60:63], v[74:77], v[18:33]
	s_waitcnt lgkmcnt(2)
	v_mfma_f32_32x32x16_bf16 v[18:33], v[56:59], v[78:81], v[18:33]
	s_waitcnt lgkmcnt(0)
	v_mfma_f32_32x32x16_bf16 v[18:33], v[52:55], v[180:183], v[18:33]
	s_cbranch_vccnz .LBB0_225
	s_waitcnt vmcnt(0)
	ds_write_b128 v113, v[104:107] offset:8192
	ds_write_b128 v117, v[100:103] offset:24576

.LBB0_233:
	ds_read_b64_tr_b16 v[54:55], v139 offset:0
	ds_read_b64_tr_b16 v[56:57], v139 offset:0x400
	ds_read_b64_tr_b16 v[58:59], v139 offset:0x800
	ds_read_b64_tr_b16 v[60:61], v139 offset:0xc00
	ds_read_b64_tr_b16 v[62:63], v139 offset:0x1000
	ds_read_b64_tr_b16 v[64:65], v139 offset:0x1400
	ds_read_b64_tr_b16 v[70:71], v139 offset:0x1800
	ds_read_b64_tr_b16 v[72:73], v139 offset:0x1c00
	s_nop 0
	s_waitcnt lgkmcnt(6)
	v_mfma_f32_32x32x16_bf16 v[2:17], v[48:51], v[54:57], v[2:17]
	ds_read_b64_tr_b16 v[54:55], v139 offset:0x200
	ds_read_b64_tr_b16 v[56:57], v139 offset:0x600
	s_waitcnt lgkmcnt(6)
	v_mfma_f32_32x32x16_bf16 v[2:17], v[44:47], v[58:61], v[2:17]
	ds_read_b64_tr_b16 v[58:59], v139 offset:0xa00
	ds_read_b64_tr_b16 v[60:61], v139 offset:0xe00
	s_waitcnt lgkmcnt(6)
	v_mfma_f32_32x32x16_bf16 v[2:17], v[40:43], v[62:65], v[2:17]
	ds_read_b64_tr_b16 v[62:63], v139 offset:0x1200
	ds_read_b64_tr_b16 v[64:65], v139 offset:0x1600
	s_waitcnt lgkmcnt(6)
	v_mfma_f32_32x32x16_bf16 v[2:17], v[36:39], v[70:73], v[2:17]
	ds_read_b64_tr_b16 v[70:71], v139 offset:0x1a00
	ds_read_b64_tr_b16 v[72:73], v139 offset:0x1e00
	s_waitcnt lgkmcnt(6)
	v_mfma_f32_32x32x16_bf16 v[18:33], v[48:51], v[54:57], v[18:33]
	s_andn2_b64 vcc, exec, s[8:9]
	s_waitcnt lgkmcnt(4)
	v_mfma_f32_32x32x16_bf16 v[18:33], v[44:47], v[58:61], v[18:33]
	s_waitcnt lgkmcnt(2)
	v_mfma_f32_32x32x16_bf16 v[18:33], v[40:43], v[62:65], v[18:33]
	s_waitcnt lgkmcnt(0)
	v_mfma_f32_32x32x16_bf16 v[18:33], v[36:39], v[70:73], v[18:33]
	s_cbranch_vccnz .LBB0_235
	s_waitcnt vmcnt(0)
	ds_write_b128 v113, v[104:107]
	ds_write_b128 v117, v[100:103] offset:16384

.LBB0_242:
	s_add_i32 s40, s39, 4
	s_and_b32 s40, s40, 1
	s_add_i32 s41, s41, -4
	v_cmp_ge_i32_e32 vcc, s41, v173
	v_cmp_lt_i32_e64 s[74:75], s41, v174
	s_and_b64 vcc, vcc, s[74:75]
	s_and_saveexec_b64 s[74:75], vcc
	s_cbranch_execz .LBB0_249
	s_lshl_b32 s41, s40, 13
	v_add_u32_e32 v82, s41, v136
	v_add_u32_e32 v50, v82, v130
	ds_read_b128 v[66:69], v50 offset:16384
	ds_read_b128 v[180:183], v50 offset:20480
	v_add_u32_e32 v83, v82, v131
	v_add_u32_e32 v128, v175, v169
	v_readlane_b32 vcc_lo, v254, 22
	s_waitcnt lgkmcnt(1)
	v_mfma_f32_32x32x16_bf16 v[50:65], v[66:69], v[84:87], v[34:49]
	v_readlane_b32 vcc_hi, v254, 23
	s_waitcnt lgkmcnt(0)
	v_mfma_f32_32x32x16_bf16 v[66:81], v[180:183], v[84:87], v[34:49]
	ds_read_b128 v[180:183], v83 offset:16384
	ds_read_b128 v[184:187], v83 offset:20480
	v_add_u32_e32 v83, v82, v132
	v_add_u32_e32 v82, v82, v133
	s_waitcnt lgkmcnt(0)
	v_mfma_f32_32x32x16_bf16 v[66:81], v[184:187], v[88:91], v[66:81]
	v_mfma_f32_32x32x16_bf16 v[50:65], v[180:183], v[88:91], v[50:65]
	ds_read_b128 v[180:183], v83 offset:16384
	ds_read_b128 v[184:187], v83 offset:20480
	v_add_u32_e32 v83, v175, v171
	s_waitcnt lgkmcnt(0)
	v_mfma_f32_32x32x16_bf16 v[66:81], v[184:187], v[92:95], v[66:81]
	v_mfma_f32_32x32x16_bf16 v[50:65], v[180:183], v[92:95], v[50:65]
	ds_read_b128 v[180:183], v82 offset:16384
	ds_read_b128 v[184:187], v82 offset:20480
	v_add_u32_e32 v82, v175, v172
	ds_read_b32 v82, v82 offset:35260
	ds_read_b32 v83, v83 offset:35260
	ds_read_b32 v128, v128 offset:35260
	s_waitcnt lgkmcnt(3)
	v_mfma_f32_32x32x16_bf16 v[66:81], v[184:187], v[96:99], v[66:81]
	v_mfma_f32_32x32x16_bf16 v[50:65], v[180:183], v[96:99], v[50:65]
	s_waitcnt lgkmcnt(1)
	s_nop 9
	v_add_f32_e32 v66, v66, v83
	v_add_u32_e32 v83, v175, v170
	ds_read_b32 v83, v83 offset:35260
	v_cndmask_b32_e32 v66, v218, v66, vcc
	v_readlane_b32 vcc_lo, v254, 26
	v_readlane_b32 vcc_hi, v254, 27
	s_waitcnt lgkmcnt(0)
	v_pk_add_f32 v[82:83], v[50:51], v[82:83]
	s_nop 0
	v_cndmask_b32_e32 v51, v82, v218, vcc
	v_readlane_b32 vcc_lo, v254, 24
	v_readlane_b32 vcc_hi, v254, 25
	v_add_f32_e32 v50, v67, v128
	s_nop 0
	v_cndmask_b32_e32 v82, v83, v218, vcc
	v_readlane_b32 vcc_lo, v254, 28
	v_readlane_b32 vcc_hi, v254, 29
	s_nop 1
	v_cndmask_b32_e32 v67, v218, v50, vcc
	v_add_u32_e32 v50, v175, v168
	ds_read_b32 v128, v50 offset:35260
	v_add_u32_e32 v50, v175, v167
	ds_read_b32 v50, v50 offset:35260
	v_readlane_b32 vcc_lo, v254, 30
	v_readlane_b32 vcc_hi, v254, 31
	s_waitcnt lgkmcnt(0)
	v_add_f32_e32 v50, v68, v50
	v_cndmask_b32_e32 v68, v218, v50, vcc
	v_add_u32_e32 v50, v175, v166
	ds_read_b32 v129, v50 offset:35260
	v_add_u32_e32 v50, v175, v165
	ds_read_b32 v50, v50 offset:35260
	v_readlane_b32 vcc_lo, v254, 34
	v_readlane_b32 vcc_hi, v254, 35
	s_waitcnt lgkmcnt(1)
	v_pk_add_f32 v[52:53], v[52:53], v[128:129]
	s_waitcnt lgkmcnt(0)
	v_add_f32_e32 v50, v69, v50
	v_cndmask_b32_e32 v83, v52, v218, vcc
	v_readlane_b32 vcc_lo, v254, 32
	v_readlane_b32 vcc_hi, v254, 33
	s_nop 1
	v_cndmask_b32_e32 v128, v53, v218, vcc
	v_readlane_b32 vcc_lo, v254, 36
	v_readlane_b32 vcc_hi, v254, 37
	s_nop 1
	v_cndmask_b32_e32 v69, v218, v50, vcc
	v_add_u32_e32 v50, v175, v164
	ds_read_b32 v180, v50 offset:35260
	v_add_u32_e32 v50, v175, v163
	ds_read_b32 v50, v50 offset:35260
	v_readlane_b32 vcc_lo, v254, 38
	v_readlane_b32 vcc_hi, v254, 39
	s_waitcnt lgkmcnt(0)
	v_add_f32_e32 v50, v70, v50
	v_cndmask_b32_e32 v52, v218, v50, vcc
	v_add_u32_e32 v50, v175, v162
	ds_read_b32 v181, v50 offset:35260
	v_add_u32_e32 v50, v175, v161
	ds_read_b32 v50, v50 offset:35260
	v_readlane_b32 vcc_lo, v254, 42
	v_readlane_b32 vcc_hi, v254, 43
	s_waitcnt lgkmcnt(1)
	v_pk_add_f32 v[54:55], v[54:55], v[180:181]
	s_waitcnt lgkmcnt(0)
	v_add_f32_e32 v50, v71, v50
	v_cndmask_b32_e32 v129, v54, v218, vcc
	v_readlane_b32 vcc_lo, v254, 40
	v_readlane_b32 vcc_hi, v254, 41
	s_nop 1
	v_cndmask_b32_e32 v54, v55, v218, vcc
	v_readlane_b32 vcc_lo, v254, 44
	v_readlane_b32 vcc_hi, v254, 45
	s_nop 1
	v_cndmask_b32_e32 v53, v218, v50, vcc
	v_add_u32_e32 v50, v175, v160
	ds_read_b32 v180, v50 offset:35260
	v_add_u32_e32 v50, v175, v159
	ds_read_b32 v50, v50 offset:35260
	v_readlane_b32 vcc_lo, v254, 46
	v_readlane_b32 vcc_hi, v254, 47
	s_waitcnt lgkmcnt(0)
	v_add_f32_e32 v50, v72, v50
	v_cndmask_b32_e32 v70, v218, v50, vcc
	v_add_u32_e32 v50, v175, v158
	ds_read_b32 v181, v50 offset:35260
	v_add_u32_e32 v50, v175, v157
	ds_read_b32 v50, v50 offset:35260
	v_readlane_b32 vcc_lo, v254, 50
	v_readlane_b32 vcc_hi, v254, 51
	s_waitcnt lgkmcnt(1)
	v_pk_add_f32 v[56:57], v[56:57], v[180:181]
	s_nop 0
	v_cndmask_b32_e32 v55, v56, v218, vcc
	v_readlane_b32 vcc_lo, v254, 48
	v_readlane_b32 vcc_hi, v254, 49
	s_nop 1
	v_cndmask_b32_e32 v56, v57, v218, vcc
	v_readlane_b32 vcc_lo, v254, 52
	v_add_u32_e32 v57, v175, v155
	v_readlane_b32 vcc_hi, v254, 53
	ds_read_b32 v180, v57 offset:35260
	s_waitcnt lgkmcnt(1)
	v_add_f32_e32 v50, v73, v50
	v_cndmask_b32_e32 v71, v218, v50, vcc
	v_add_u32_e32 v50, v175, v156
	ds_read_b32 v50, v50 offset:35260
	v_readlane_b32 vcc_lo, v254, 54
	v_readlane_b32 vcc_hi, v254, 55
	v_add_u32_e32 v73, v175, v151
	s_waitcnt lgkmcnt(0)
	v_add_f32_e32 v50, v58, v50
	v_cndmask_b32_e32 v57, v218, v50, vcc
	v_add_u32_e32 v50, v175, v154
	ds_read_b32 v50, v50 offset:35260
	v_add_u32_e32 v58, v175, v153
	ds_read_b32 v181, v58 offset:35260
	s_waitcnt lgkmcnt(1)
	v_add_f32_e32 v50, v59, v50
	v_cndmask_b32_e64 v72, v218, v50, s[44:45]
	v_add_u32_e32 v50, v175, v152
	ds_read_b32 v50, v50 offset:35260
	s_waitcnt lgkmcnt(1)
	v_pk_add_f32 v[58:59], v[74:75], v[180:181]
	ds_read_b32 v180, v73 offset:35260
	v_add_u32_e32 v75, v175, v147
	v_cndmask_b32_e64 v59, v218, v59, s[10:11]
	s_waitcnt lgkmcnt(1)
	v_add_f32_e32 v50, v60, v50
	v_cndmask_b32_e64 v73, v218, v50, s[50:51]
	v_add_u32_e32 v50, v175, v150
	ds_read_b32 v50, v50 offset:35260
	v_add_u32_e32 v60, v175, v149
	ds_read_b32 v181, v60 offset:35260
	v_cndmask_b32_e64 v58, v218, v58, s[12:13]
	s_waitcnt lgkmcnt(1)
	v_add_f32_e32 v50, v61, v50
	v_cndmask_b32_e64 v74, v218, v50, s[52:53]
	v_add_u32_e32 v50, v175, v148
	ds_read_b32 v50, v50 offset:35260
	s_waitcnt lgkmcnt(1)
	v_pk_add_f32 v[60:61], v[76:77], v[180:181]
	ds_read_b32 v180, v75 offset:35260
	v_add_u32_e32 v77, v175, v143
	v_cndmask_b32_e64 v61, v218, v61, s[14:15]
	s_waitcnt lgkmcnt(1)
	v_add_f32_e32 v50, v62, v50
	v_cndmask_b32_e64 v75, v218, v50, s[58:59]
	v_add_u32_e32 v50, v175, v146
	ds_read_b32 v50, v50 offset:35260
	v_add_u32_e32 v62, v175, v145
	ds_read_b32 v181, v62 offset:35260
	v_cndmask_b32_e64 v60, v218, v60, s[16:17]
	s_waitcnt lgkmcnt(1)
	v_add_f32_e32 v50, v63, v50
	v_cndmask_b32_e64 v76, v218, v50, s[60:61]
	v_add_u32_e32 v50, v175, v144
	ds_read_b32 v50, v50 offset:35260
	s_waitcnt lgkmcnt(1)
	v_pk_add_f32 v[62:63], v[78:79], v[180:181]
	ds_read_b32 v78, v77 offset:35260
	v_cndmask_b32_e64 v63, v218, v63, s[18:19]
	v_cndmask_b32_e64 v62, v218, v62, s[20:21]
	s_waitcnt lgkmcnt(1)
	v_add_f32_e32 v50, v64, v50
	v_add_u32_e32 v64, v175, v142
	v_cndmask_b32_e64 v77, v218, v50, s[66:67]
	s_waitcnt lgkmcnt(0)
	v_add_f32_e32 v50, v80, v78
	ds_read_b32 v64, v64 offset:35260
	v_add_u32_e32 v78, v175, v140
	ds_read_b32 v78, v78 offset:35260
	v_cndmask_b32_e64 v50, v218, v50, s[22:23]
	s_waitcnt lgkmcnt(1)
	v_add_f32_e32 v64, v65, v64
	v_cndmask_b32_e64 v65, v218, v64, s[70:71]
	s_waitcnt lgkmcnt(0)
	v_add_f32_e32 v64, v81, v78
	v_max_f32_e32 v78, v51, v82
	v_max3_f32 v78, v78, v83, v128
	v_max3_f32 v78, v78, v129, v54
	v_max3_f32 v78, v78, v55, v56
	v_max3_f32 v78, v78, v57, v72
	v_max3_f32 v78, v78, v73, v74
	v_max3_f32 v78, v78, v75, v76
	v_max3_f32 v78, v78, v77, v65
	v_max3_f32 v78, v78, v66, v67
	v_max3_f32 v78, v78, v68, v69
	v_max3_f32 v78, v78, v52, v53
	v_max3_f32 v78, v78, v70, v71
	v_max3_f32 v78, v78, v58, v59
	v_max3_f32 v78, v78, v60, v61
	v_cndmask_b32_e64 v64, v218, v64, s[30:31]
	v_max3_f32 v78, v78, v62, v63
	v_max3_f32 v78, v78, v50, v64
	v_mov_b32_e32 v79, v78
	s_nop 1
	v_permlane32_swap_b32_e32 v78, v79
	v_max_f32_e32 v79, v79, v79
	v_max_f32_e32 v78, v78, v78
	v_max_f32_e32 v79, v78, v79
	v_cmp_ge_f32_e32 vcc, s64, v79
	v_mov_b32_e32 v78, 1.0
	s_cmp_eq_u64 vcc, exec
	s_cbranch_scc0 .LBB0_251

.LBB0_248:
	v_add_f32_e32 v82, v66, v67
	v_fmac_f32_e32 v82, v176, v78
	v_add_u32_e32 v83, s41, v135
	ds_read_b64_tr_b16 v[66:67], v83 offset:0
	ds_read_b64_tr_b16 v[68:69], v83 offset:0x400
	ds_read_b64_tr_b16 v[70:71], v83 offset:0x800
	ds_read_b64_tr_b16 v[72:73], v83 offset:0xc00
	ds_read_b64_tr_b16 v[74:75], v83 offset:0x1000
	ds_read_b64_tr_b16 v[76:77], v83 offset:0x1400
	ds_read_b64_tr_b16 v[78:79], v83 offset:0x1800
	ds_read_b64_tr_b16 v[80:81], v83 offset:0x1c00
	s_nop 0
	s_waitcnt lgkmcnt(6)
	v_mfma_f32_32x32x16_bf16 v[2:17], v[62:65], v[66:69], v[2:17]
	ds_read_b64_tr_b16 v[66:67], v83 offset:0x200
	ds_read_b64_tr_b16 v[68:69], v83 offset:0x600
	s_waitcnt lgkmcnt(6)
	v_mfma_f32_32x32x16_bf16 v[2:17], v[58:61], v[70:73], v[2:17]
	ds_read_b64_tr_b16 v[70:71], v83 offset:0xa00
	ds_read_b64_tr_b16 v[72:73], v83 offset:0xe00
	s_waitcnt lgkmcnt(6)
	v_mfma_f32_32x32x16_bf16 v[2:17], v[54:57], v[74:77], v[2:17]
	ds_read_b64_tr_b16 v[74:75], v83 offset:0x1200
	ds_read_b64_tr_b16 v[76:77], v83 offset:0x1600
	s_waitcnt lgkmcnt(6)
	v_mfma_f32_32x32x16_bf16 v[2:17], v[50:53], v[78:81], v[2:17]
	ds_read_b64_tr_b16 v[78:79], v83 offset:0x1a00
	ds_read_b64_tr_b16 v[80:81], v83 offset:0x1e00
	s_waitcnt lgkmcnt(6)
	v_mfma_f32_32x32x16_bf16 v[18:33], v[62:65], v[66:69], v[18:33]
	v_mov_b32_e32 v176, v82
	s_waitcnt lgkmcnt(4)
	v_mfma_f32_32x32x16_bf16 v[18:33], v[58:61], v[70:73], v[18:33]
	s_waitcnt lgkmcnt(2)
	v_mfma_f32_32x32x16_bf16 v[18:33], v[54:57], v[74:77], v[18:33]
	s_waitcnt lgkmcnt(0)
	v_mfma_f32_32x32x16_bf16 v[18:33], v[50:53], v[78:81], v[18:33]
